# GQA loop unrolled x2 with immediate slot offsets, LDS staging moved behind the QK MFMA chain, peeled tail
# speedup vs baseline: 1.0038x; 1.0038x over previous
; __device__ __forceinline__ unsigned pk2(float lo, float hi) { f32x2_t v = {lo, hi}; bf16x2_t b = __builtin_convertvector(v, bf16x2_t); return __builtin_bit_cast(unsigned, b); }
; __device__ __forceinline__ float fexp2(float x) { return __builtin_amdgcn_exp2f(x); }
; template <int DQK, int DV>
; __device__ __forceinline__ void attn_pass2(const bf16_t* __restrict__ qh, const bf16_t* __restrict__ kh, const bf16_t* __restrict__ vth, int q0, char* smem, f32x16 (&o)[2][DV / 32], float kmax, int wvp) {
;     ...
;   for (int kt = 0; kt < NT; ++kt) {
;     const int cur = kt & 1;
;     __syncthreads();
;     if (kt + 1 < NT) { STOREKV(cur ^ 1); if (kt + 2 < NT) LOADKV(kt + 2); }
;     f32x16 s[2][2];
;     const char* kb0 = sK + cur * KSB + kofs;
; #pragma unroll
;     for (int ks = 0; ks < NKS; ++ks) {
;       const bf16x8 a0 = *(const bf16x8*)(kb0 + ks * 32), a1 = *(const bf16x8*)(kb0 + 32 * KP + ks * 32);
; #pragma unroll
;       for (int qb = 0; qb < 2; ++qb) {
;         if (ks == 0) {
;           f32x16 z;
; #pragma unroll
;           for (int i = 0; i < 16; ++i) z[i] = 0.f;
;           s[qb][0] = MFMA(a0, qf[qb][0], z); s[qb][1] = MFMA(a1, qf[qb][0], z);
;         } else { s[qb][0] = MFMA(a0, qf[qb][ks], s[qb][0]); s[qb][1] = MFMA(a1, qf[qb][ks], s[qb][1]); }
;       }
;     }
;     __builtin_amdgcn_sched_barrier(0);
; #pragma unroll
;     for (int qb = 0; qb < 2; ++qb) {
;       float rs0 = 0.f, rs1 = 0.f;
; #pragma unroll
;       for (int i = 0; i < 16; ++i) { s[qb][0][i] = fexp2(s[qb][0][i] - mref[qb]); s[qb][1][i] = fexp2(s[qb][1][i] - mref[qb]); rs0 += s[qb][0][i]; rs1 += s[qb][1][i]; }
;       l_run[qb] += rs0 + rs1;
;     }
;     const char* vb0 = sV + cur * VSB + vofs;
; #pragma unroll
;     for (int kb = 0; kb < 2; ++kb)
; #pragma unroll
;       for (int s2 = 0; s2 < 2; ++s2) {
;         bf16x8 pq[2];
; #pragma unroll
;         for (int qb = 0; qb < 2; ++qb) {
;           u32x4 w;
;           w.x = pk2(s[qb][kb][8 * s2 + 0], s[qb][kb][8 * s2 + 1]); w.y = pk2(s[qb][kb][8 * s2 + 2], s[qb][kb][8 * s2 + 3]);
;           w.z = pk2(s[qb][kb][8 * s2 + 4], s[qb][kb][8 * s2 + 5]); w.w = pk2(s[qb][kb][8 * s2 + 6], s[qb][kb][8 * s2 + 7]);
;           pq[qb] = __builtin_bit_cast(bf16x8, w);
;         }
; #pragma unroll
;         for (int eb = 0; eb < NEB; ++eb) {
;           const bf16x8 a = *(const bf16x8*)(vb0 + eb * 32 * VP + (32 * kb + 16 * s2) * 2);
.LBB0_1430:
	s_waitcnt lgkmcnt(0)
	s_barrier
	ds_read_b128 v[64:67], v169
	ds_read_b128 v[176:179], v169 offset:32
	ds_read_b128 v[68:71], v169 offset:4608
	ds_read_b128 v[192:195], v169 offset:4640
	s_waitcnt lgkmcnt(3)
	v_mfma_f32_32x32x16_bf16 v[112:127], v[64:67], v[128:131], v[236:251]
	s_waitcnt lgkmcnt(1)
	v_mfma_f32_32x32x16_bf16 v[96:111], v[68:71], v[128:131], v[236:251]
	v_mfma_f32_32x32x16_bf16 v[80:95], v[64:67], v[144:147], v[236:251]
	v_mfma_f32_32x32x16_bf16 v[64:79], v[68:71], v[144:147], v[236:251]
	v_mfma_f32_32x32x16_bf16 v[112:127], v[176:179], v[132:135], v[112:127]
	s_waitcnt lgkmcnt(0)
	v_mfma_f32_32x32x16_bf16 v[96:111], v[192:195], v[132:135], v[96:111]
	v_mfma_f32_32x32x16_bf16 v[80:95], v[176:179], v[148:151], v[80:95]
	v_mfma_f32_32x32x16_bf16 v[64:79], v[192:195], v[148:151], v[64:79]
	ds_read_b128 v[176:179], v169 offset:64
	ds_read_b128 v[192:195], v169 offset:96
	ds_read_b128 v[196:199], v169 offset:4672
	ds_read_b128 v[200:203], v169 offset:4704
	s_waitcnt lgkmcnt(3)
	v_mfma_f32_32x32x16_bf16 v[112:127], v[176:179], v[136:139], v[112:127]
	s_waitcnt lgkmcnt(1)
	v_mfma_f32_32x32x16_bf16 v[96:111], v[196:199], v[136:139], v[96:111]
	v_mfma_f32_32x32x16_bf16 v[80:95], v[176:179], v[152:155], v[80:95]
	v_mfma_f32_32x32x16_bf16 v[64:79], v[196:199], v[152:155], v[64:79]
	v_mfma_f32_32x32x16_bf16 v[112:127], v[192:195], v[140:143], v[112:127]
	s_waitcnt lgkmcnt(0)
	v_mfma_f32_32x32x16_bf16 v[96:111], v[200:203], v[140:143], v[96:111]
	v_mfma_f32_32x32x16_bf16 v[80:95], v[192:195], v[156:159], v[80:95]
	v_mfma_f32_32x32x16_bf16 v[64:79], v[200:203], v[156:159], v[64:79]
	s_waitcnt vmcnt(1)
	ds_write_b128 v184, v[160:163] offset:9216
	s_waitcnt vmcnt(0)
	ds_write_b128 v168, v[164:167] offset:27648
	global_load_dwordx4 v[160:163], v[170:171], off
	global_load_dwordx4 v[164:167], v[172:173], off
	v_lshl_add_u64 v[170:171], v[170:171], 0, s[52:53]
	v_lshl_add_u64 v[172:173], v[172:173], 0, s[54:55]
	s_nop 1
	v_exp_f32_e32 v186, v96
	v_exp_f32_e32 v97, v97
	v_exp_f32_e32 v177, v112
	v_exp_f32_e32 v113, v113
	v_exp_f32_e32 v179, v114
	v_exp_f32_e32 v187, v98
	v_add_f32_e32 v98, v97, v186
	v_exp_f32_e32 v115, v115
	v_exp_f32_e32 v190, v99
	v_exp_f32_e32 v204, v100
	v_exp_f32_e32 v99, v116
	v_exp_f32_e32 v117, v117
	v_add_f32_e32 v96, v113, v177
	v_exp_f32_e32 v101, v101
	v_add_f32_e32 v96, v179, v96
	v_exp_f32_e32 v181, v118
	v_add_f32_e32 v96, v115, v96
	v_add_f32_e32 v96, v99, v96
	v_add_f32_e32 v96, v117, v96
	v_add_f32_e32 v112, v181, v96
	v_exp_f32_e32 v176, v119
	v_exp_f32_e32 v178, v103
	v_add_f32_e32 v98, v187, v98
	v_exp_f32_e32 v205, v102
	v_exp_f32_e32 v180, v120
	v_exp_f32_e32 v96, v104
	v_exp_f32_e32 v104, v123
	v_add_f32_e32 v98, v190, v98
	v_exp_f32_e32 v100, v106
	v_exp_f32_e32 v106, v107
	v_add_f32_e32 v98, v204, v98
	v_exp_f32_e32 v118, v124
	v_add_f32_e32 v98, v101, v98
	v_exp_f32_e32 v120, v108
	v_add_f32_e32 v102, v205, v98
	v_exp_f32_e32 v124, v125
	v_exp_f32_e32 v116, v121
	v_exp_f32_e32 v108, v109
	v_exp_f32_e32 v114, v105
	v_exp_f32_e32 v98, v122
	v_exp_f32_e32 v122, v126
	v_exp_f32_e32 v110, v110
	v_exp_f32_e32 v126, v127
	v_exp_f32_e32 v103, v80
	v_exp_f32_e32 v107, v64
	v_exp_f32_e32 v109, v81
	v_exp_f32_e32 v65, v65
	v_exp_f32_e32 v121, v66
	v_add_f32_e32 v66, v109, v103
	v_add_f32_e32 v80, v65, v107
	v_add_f32_e32 v206, v121, v80
	v_exp_f32_e32 v207, v83
	v_exp_f32_e32 v64, v111
	v_exp_f32_e32 v111, v82
	v_exp_f32_e32 v208, v84
	ds_read_b128 v[80:83], v185 offset:18432
	ds_read_b128 v[196:199], v185 offset:18464
	ds_read_b128 v[200:203], v185 offset:23040
	v_exp_f32_e32 v212, v85
	v_exp_f32_e32 v213, v86
	v_cvt_pk_bf16_f32 v192, v177, v113
	v_exp_f32_e32 v177, v87
	v_cvt_pk_bf16_f32 v84, v103, v109
	v_exp_f32_e32 v109, v67
	v_add_f32_e32 v66, v111, v66
	v_cvt_pk_bf16_f32 v85, v111, v207
	v_exp_f32_e32 v111, v68
	v_cvt_pk_bf16_f32 v195, v181, v176
	v_exp_f32_e32 v181, v88
	v_cvt_pk_bf16_f32 v194, v99, v117
	v_exp_f32_e32 v117, v89
	v_cvt_pk_bf16_f32 v193, v179, v115
	v_cvt_pk_bf16_f32 v86, v208, v212
	v_cvt_pk_bf16_f32 v87, v213, v177
	v_exp_f32_e32 v99, v90
	s_waitcnt lgkmcnt(2)
	v_mfma_f32_32x32x16_bf16 v[48:63], v[80:83], v[192:195], v[48:63]
	v_exp_f32_e32 v105, v91
	v_exp_f32_e32 v119, v92
	v_exp_f32_e32 v125, v93
	v_mfma_f32_32x32x16_bf16 v[16:31], v[80:83], v[84:87], v[16:31]
	ds_read_b128 v[80:83], v185 offset:23072
	v_exp_f32_e32 v123, v94
	v_exp_f32_e32 v92, v69
	v_exp_f32_e32 v127, v95
	s_waitcnt lgkmcnt(1)
	v_mfma_f32_32x32x16_bf16 v[0:15], v[200:203], v[84:87], v[0:15]
	v_exp_f32_e32 v93, v70
	v_add_f32_e32 v66, v207, v66
	v_add_f32_e32 v67, v109, v206
	v_add_f32_e32 v66, v208, v66
	v_add_f32_e32 v67, v111, v67
	v_add_f32_e32 v66, v212, v66
	v_add_f32_e32 v67, v92, v67
	v_mfma_f32_32x32x16_bf16 v[32:47], v[200:203], v[192:195], v[32:47]
	v_cvt_pk_bf16_f32 v84, v180, v116
	v_cvt_pk_bf16_f32 v85, v98, v104
	v_cvt_pk_bf16_f32 v86, v118, v124
	v_cvt_pk_bf16_f32 v87, v122, v126
	v_cvt_pk_bf16_f32 v88, v181, v117
	v_cvt_pk_bf16_f32 v89, v99, v105
	v_cvt_pk_bf16_f32 v90, v119, v125
	v_cvt_pk_bf16_f32 v91, v123, v127
	v_add_f32_e32 v113, v213, v66
	v_add_f32_e32 v103, v93, v67
	ds_read_b128 v[66:69], v185 offset:18496
	v_mfma_f32_32x32x16_bf16 v[48:63], v[196:199], v[84:87], v[48:63]
	v_exp_f32_e32 v179, v71
	v_mov_b32_e32 v70, v72
	v_exp_f32_e32 v115, v73
	v_cvt_pk_bf16_f32 v71, v121, v109
	v_cvt_pk_bf16_f32 v72, v111, v92
	v_cvt_pk_bf16_f32 v73, v93, v179
	v_mfma_f32_32x32x16_bf16 v[16:31], v[196:199], v[88:91], v[16:31]
	s_waitcnt lgkmcnt(1)
; __device__ __forceinline__ float fexp2(float x) { return __builtin_amdgcn_exp2f(x); }
; template <int DQK, int DV>
; __device__ __forceinline__ void attn_pass2(const bf16_t* __restrict__ qh, const bf16_t* __restrict__ kh, const bf16_t* __restrict__ vth, int q0, char* smem, f32x16 (&o)[2][DV / 32], float kmax, int wvp) {
;     ...
;   for (int kt = 0; kt < NT; ++kt) {
;     const int cur = kt & 1;
;     __syncthreads();
;     if (kt + 1 < NT) { STOREKV(cur ^ 1); if (kt + 2 < NT) LOADKV(kt + 2); }
;     f32x16 s[2][2];
;     const char* kb0 = sK + cur * KSB + kofs;
; #pragma unroll
;     for (int ks = 0; ks < NKS; ++ks) {
;       const bf16x8 a0 = *(const bf16x8*)(kb0 + ks * 32), a1 = *(const bf16x8*)(kb0 + 32 * KP + ks * 32);
; #pragma unroll
;       for (int qb = 0; qb < 2; ++qb) {
;         if (ks == 0) {
;           f32x16 z;
; #pragma unroll
;           for (int i = 0; i < 16; ++i) z[i] = 0.f;
;           s[qb][0] = MFMA(a0, qf[qb][0], z); s[qb][1] = MFMA(a1, qf[qb][0], z);
;         } else { s[qb][0] = MFMA(a0, qf[qb][ks], s[qb][0]); s[qb][1] = MFMA(a1, qf[qb][ks], s[qb][1]); }
;       }
;     }
;     __builtin_amdgcn_sched_barrier(0);
; #pragma unroll
;     for (int qb = 0; qb < 2; ++qb) {
;       float rs0 = 0.f, rs1 = 0.f;
; #pragma unroll
;       for (int i = 0; i < 16; ++i) { s[qb][0][i] = fexp2(s[qb][0][i] - mref[qb]); s[qb][1][i] = fexp2(s[qb][1][i] - mref[qb]); rs0 += s[qb][0][i]; rs1 += s[qb][1][i]; }
;       l_run[qb] += rs0 + rs1;
;     }
;     const char* vb0 = sV + cur * VSB + vofs;
; #pragma unroll
;     for (int kb = 0; kb < 2; ++kb)
; #pragma unroll
;       for (int s2 = 0; s2 < 2; ++s2) {
;         bf16x8 pq[2];
; #pragma unroll
;         for (int qb = 0; qb < 2; ++qb) {
;           u32x4 w;
;           w.x = pk2(s[qb][kb][8 * s2 + 0], s[qb][kb][8 * s2 + 1]); w.y = pk2(s[qb][kb][8 * s2 + 2], s[qb][kb][8 * s2 + 3]);
;           w.z = pk2(s[qb][kb][8 * s2 + 4], s[qb][kb][8 * s2 + 5]); w.w = pk2(s[qb][kb][8 * s2 + 6], s[qb][kb][8 * s2 + 7]);
;           pq[qb] = __builtin_bit_cast(bf16x8, w);
;         }
; #pragma unroll
;         for (int eb = 0; eb < NEB; ++eb) {
;           const bf16x8 a = *(const bf16x8*)(vb0 + eb * 32 * VP + (32 * kb + 16 * s2) * 2);
; #pragma unroll
;           for (int qb = 0; qb < 2; ++qb) o[qb][eb] = MFMA(a, pq[qb], o[qb][eb]);
;         }
;       }
;   }
	v_mfma_f32_32x32x16_bf16 v[0:15], v[80:83], v[88:91], v[0:15]
	ds_read_b128 v[88:91], v185 offset:23104
	v_mfma_f32_32x32x16_bf16 v[32:47], v[80:83], v[84:87], v[32:47]
	v_cvt_pk_bf16_f32 v80, v186, v97
	v_exp_f32_e32 v97, v70
	v_cvt_pk_bf16_f32 v70, v107, v65
	v_cvt_pk_bf16_f32 v81, v187, v190
	v_cvt_pk_bf16_f32 v82, v204, v101
	v_cvt_pk_bf16_f32 v83, v205, v178
	v_exp_f32_e32 v101, v74
	ds_read_b128 v[84:87], v185 offset:18528
	s_waitcnt lgkmcnt(2)
	v_mfma_f32_32x32x16_bf16 v[48:63], v[66:69], v[80:83], v[48:63]
	v_exp_f32_e32 v107, v75
	v_exp_f32_e32 v121, v76
	v_exp_f32_e32 v109, v77
	v_exp_f32_e32 v111, v78
	v_mfma_f32_32x32x16_bf16 v[16:31], v[66:69], v[70:73], v[16:31]
	ds_read_b128 v[66:69], v185 offset:23136
	v_exp_f32_e32 v65, v79
	v_add_f32_e32 v74, v178, v102
	v_add_f32_e32 v75, v179, v103
	s_nop 0
	v_add_f32_e32 v74, v96, v74
	v_add_f32_e32 v75, v97, v75
	s_waitcnt lgkmcnt(2)
	v_mfma_f32_32x32x16_bf16 v[32:47], v[88:91], v[80:83], v[32:47]
	v_add_f32_e64 v80, v114, v74
	v_add_f32_e64 v81, v115, v75
	v_cvt_pk_bf16_f32 v74, v97, v115
	v_cvt_pk_bf16_f32 v75, v101, v107
	v_add_f32_e64 v80, v100, v80
	v_add_f32_e64 v81, v101, v81
	v_add_f32_e32 v80, v106, v80
	v_add_f32_e32 v81, v107, v81
	v_mfma_f32_32x32x16_bf16 v[0:15], v[88:91], v[70:73], v[0:15]
	v_add_f32_e64 v70, v176, v112
	v_add_f32_e64 v71, v177, v113
	v_cvt_pk_bf16_f32 v72, v120, v108
	v_add_f32_e64 v76, v180, v70
	v_add_f32_e64 v77, v181, v71
	v_cvt_pk_bf16_f32 v70, v96, v114
	v_cvt_pk_bf16_f32 v71, v100, v106
	v_cvt_pk_bf16_f32 v73, v110, v64
	v_add_f32_e32 v78, v116, v76
	v_add_f32_e32 v79, v117, v77
	v_cvt_pk_bf16_f32 v76, v121, v109
	v_cvt_pk_bf16_f32 v77, v111, v65
	s_waitcnt lgkmcnt(1)
	v_mfma_f32_32x32x16_bf16 v[48:63], v[84:87], v[70:73], v[48:63]
	v_add_f32_e64 v78, v98, v78
	v_add_f32_e64 v79, v99, v79
	v_add_f32_e64 v80, v120, v80
	v_add_f32_e64 v81, v121, v81
	v_add_f32_e64 v78, v104, v78
	v_add_f32_e64 v79, v105, v79
	v_add_f32_e32 v78, v118, v78
	v_add_f32_e32 v79, v119, v79
	s_nop 0
	v_add_f32_e32 v78, v124, v78
	v_add_f32_e32 v79, v125, v79
	v_mfma_f32_32x32x16_bf16 v[16:31], v[84:87], v[74:77], v[16:31]
	s_waitcnt lgkmcnt(0)
	v_mfma_f32_32x32x16_bf16 v[32:47], v[66:69], v[70:73], v[32:47]
	v_add_f32_e64 v70, v108, v80
	v_add_f32_e64 v71, v109, v81
	v_add_f32_e64 v72, v122, v78
	v_add_f32_e64 v73, v123, v79
	v_add_f32_e64 v70, v110, v70
	v_add_f32_e64 v71, v111, v71
	v_add_f32_e32 v72, v126, v72
	v_add_f32_e32 v73, v127, v73
	v_add_f32_e32 v64, v64, v70
	v_add_f32_e32 v65, v65, v71
	s_nop 0
	v_add_f32_e32 v64, v72, v64
	v_add_f32_e32 v65, v73, v65
	v_mfma_f32_32x32x16_bf16 v[0:15], v[66:69], v[74:77], v[0:15]
	v_add_f32_e64 v174, v174, v64
	v_add_f32_e64 v175, v175, v65
	s_waitcnt lgkmcnt(0)
	s_barrier
	ds_read_b128 v[64:67], v169 offset:9216
	ds_read_b128 v[176:179], v169 offset:9248
	ds_read_b128 v[68:71], v169 offset:13824
	ds_read_b128 v[192:195], v169 offset:13856
	s_waitcnt lgkmcnt(3)
	v_mfma_f32_32x32x16_bf16 v[112:127], v[64:67], v[128:131], v[236:251]
	s_waitcnt lgkmcnt(1)
	v_mfma_f32_32x32x16_bf16 v[96:111], v[68:71], v[128:131], v[236:251]
	v_mfma_f32_32x32x16_bf16 v[80:95], v[64:67], v[144:147], v[236:251]
	v_mfma_f32_32x32x16_bf16 v[64:79], v[68:71], v[144:147], v[236:251]
	v_mfma_f32_32x32x16_bf16 v[112:127], v[176:179], v[132:135], v[112:127]
	s_waitcnt lgkmcnt(0)
	v_mfma_f32_32x32x16_bf16 v[96:111], v[192:195], v[132:135], v[96:111]
	v_mfma_f32_32x32x16_bf16 v[80:95], v[176:179], v[148:151], v[80:95]
	v_mfma_f32_32x32x16_bf16 v[64:79], v[192:195], v[148:151], v[64:79]
	ds_read_b128 v[176:179], v169 offset:9280
	ds_read_b128 v[192:195], v169 offset:9312
	ds_read_b128 v[196:199], v169 offset:13888
	ds_read_b128 v[200:203], v169 offset:13920
	s_waitcnt lgkmcnt(3)
	v_mfma_f32_32x32x16_bf16 v[112:127], v[176:179], v[136:139], v[112:127]
	s_waitcnt lgkmcnt(1)
	v_mfma_f32_32x32x16_bf16 v[96:111], v[196:199], v[136:139], v[96:111]
	v_mfma_f32_32x32x16_bf16 v[80:95], v[176:179], v[152:155], v[80:95]
	v_mfma_f32_32x32x16_bf16 v[64:79], v[196:199], v[152:155], v[64:79]
	v_mfma_f32_32x32x16_bf16 v[112:127], v[192:195], v[140:143], v[112:127]
	s_waitcnt lgkmcnt(0)
	v_mfma_f32_32x32x16_bf16 v[96:111], v[200:203], v[140:143], v[96:111]
	v_mfma_f32_32x32x16_bf16 v[80:95], v[192:195], v[156:159], v[80:95]
	v_mfma_f32_32x32x16_bf16 v[64:79], v[200:203], v[156:159], v[64:79]
	s_waitcnt vmcnt(1)
	ds_write_b128 v184, v[160:163]
	s_waitcnt vmcnt(0)
	ds_write_b128 v168, v[164:167] offset:18432
	global_load_dwordx4 v[160:163], v[170:171], off
	global_load_dwordx4 v[164:167], v[172:173], off
	v_lshl_add_u64 v[170:171], v[170:171], 0, s[52:53]
	v_lshl_add_u64 v[172:173], v[172:173], 0, s[54:55]
	s_nop 1
	v_exp_f32_e32 v186, v96
	v_exp_f32_e32 v97, v97
	v_exp_f32_e32 v177, v112
	v_exp_f32_e32 v113, v113
	v_exp_f32_e32 v179, v114
	v_exp_f32_e32 v187, v98
	v_add_f32_e32 v98, v97, v186
	v_exp_f32_e32 v115, v115
	v_exp_f32_e32 v190, v99
	v_exp_f32_e32 v204, v100
	v_exp_f32_e32 v99, v116
	v_exp_f32_e32 v117, v117
	v_add_f32_e32 v96, v113, v177
	v_exp_f32_e32 v101, v101
	v_add_f32_e32 v96, v179, v96
	v_exp_f32_e32 v181, v118
	v_add_f32_e32 v96, v115, v96
	v_add_f32_e32 v96, v99, v96
	v_add_f32_e32 v96, v117, v96
	v_add_f32_e32 v112, v181, v96
	v_exp_f32_e32 v176, v119
	v_exp_f32_e32 v178, v103
	v_add_f32_e32 v98, v187, v98
	v_exp_f32_e32 v205, v102
	v_exp_f32_e32 v180, v120
	v_exp_f32_e32 v96, v104
	v_exp_f32_e32 v104, v123
	v_add_f32_e32 v98, v190, v98
	v_exp_f32_e32 v100, v106
	v_exp_f32_e32 v106, v107
	v_add_f32_e32 v98, v204, v98
	v_exp_f32_e32 v118, v124
	v_add_f32_e32 v98, v101, v98
	v_exp_f32_e32 v120, v108
	v_add_f32_e32 v102, v205, v98
	v_exp_f32_e32 v124, v125
	v_exp_f32_e32 v116, v121
	v_exp_f32_e32 v108, v109
	v_exp_f32_e32 v114, v105
	v_exp_f32_e32 v98, v122
	v_exp_f32_e32 v122, v126
	v_exp_f32_e32 v110, v110
	v_exp_f32_e32 v126, v127
	v_exp_f32_e32 v103, v80
	v_exp_f32_e32 v107, v64
	v_exp_f32_e32 v109, v81
	v_exp_f32_e32 v65, v65
	v_exp_f32_e32 v121, v66
	v_add_f32_e32 v66, v109, v103
	v_add_f32_e32 v80, v65, v107
	v_add_f32_e32 v206, v121, v80
	v_exp_f32_e32 v207, v83
	v_exp_f32_e32 v64, v111
	v_exp_f32_e32 v111, v82
	v_exp_f32_e32 v208, v84
	ds_read_b128 v[80:83], v185 offset:27648
	ds_read_b128 v[196:199], v185 offset:27680
	ds_read_b128 v[200:203], v185 offset:32256
	v_exp_f32_e32 v212, v85
	v_exp_f32_e32 v213, v86
	v_cvt_pk_bf16_f32 v192, v177, v113
	v_exp_f32_e32 v177, v87
	v_cvt_pk_bf16_f32 v84, v103, v109
	v_exp_f32_e32 v109, v67
	v_add_f32_e32 v66, v111, v66
	v_cvt_pk_bf16_f32 v85, v111, v207
	v_exp_f32_e32 v111, v68
	v_cvt_pk_bf16_f32 v195, v181, v176
	v_exp_f32_e32 v181, v88
	v_cvt_pk_bf16_f32 v194, v99, v117
	v_exp_f32_e32 v117, v89
	v_cvt_pk_bf16_f32 v193, v179, v115
	v_cvt_pk_bf16_f32 v86, v208, v212
	v_cvt_pk_bf16_f32 v87, v213, v177
	v_exp_f32_e32 v99, v90
	s_waitcnt lgkmcnt(2)
; __device__ __forceinline__ float fexp2(float x) { return __builtin_amdgcn_exp2f(x); }
; template <int DQK, int DV>
; __device__ __forceinline__ void attn_pass2(const bf16_t* __restrict__ qh, const bf16_t* __restrict__ kh, const bf16_t* __restrict__ vth, int q0, char* smem, f32x16 (&o)[2][DV / 32], float kmax, int wvp) {
;     ...
;   for (int kt = 0; kt < NT; ++kt) {
;     const int cur = kt & 1;
;     __syncthreads();
;     if (kt + 1 < NT) { STOREKV(cur ^ 1); if (kt + 2 < NT) LOADKV(kt + 2); }
;     f32x16 s[2][2];
;     const char* kb0 = sK + cur * KSB + kofs;
; #pragma unroll
;     for (int ks = 0; ks < NKS; ++ks) {
;       const bf16x8 a0 = *(const bf16x8*)(kb0 + ks * 32), a1 = *(const bf16x8*)(kb0 + 32 * KP + ks * 32);
; #pragma unroll
;       for (int qb = 0; qb < 2; ++qb) {
;         if (ks == 0) {
;           f32x16 z;
; #pragma unroll
;           for (int i = 0; i < 16; ++i) z[i] = 0.f;
;           s[qb][0] = MFMA(a0, qf[qb][0], z); s[qb][1] = MFMA(a1, qf[qb][0], z);
;         } else { s[qb][0] = MFMA(a0, qf[qb][ks], s[qb][0]); s[qb][1] = MFMA(a1, qf[qb][ks], s[qb][1]); }
;       }
;     }
;     __builtin_amdgcn_sched_barrier(0);
; #pragma unroll
;     for (int qb = 0; qb < 2; ++qb) {
;       float rs0 = 0.f, rs1 = 0.f;
; #pragma unroll
;       for (int i = 0; i < 16; ++i) { s[qb][0][i] = fexp2(s[qb][0][i] - mref[qb]); s[qb][1][i] = fexp2(s[qb][1][i] - mref[qb]); rs0 += s[qb][0][i]; rs1 += s[qb][1][i]; }
;       l_run[qb] += rs0 + rs1;
;     }
;     const char* vb0 = sV + cur * VSB + vofs;
; #pragma unroll
;     for (int kb = 0; kb < 2; ++kb)
; #pragma unroll
;       for (int s2 = 0; s2 < 2; ++s2) {
;         bf16x8 pq[2];
; #pragma unroll
;         for (int qb = 0; qb < 2; ++qb) {
;           u32x4 w;
;           w.x = pk2(s[qb][kb][8 * s2 + 0], s[qb][kb][8 * s2 + 1]); w.y = pk2(s[qb][kb][8 * s2 + 2], s[qb][kb][8 * s2 + 3]);
;           w.z = pk2(s[qb][kb][8 * s2 + 4], s[qb][kb][8 * s2 + 5]); w.w = pk2(s[qb][kb][8 * s2 + 6], s[qb][kb][8 * s2 + 7]);
;           pq[qb] = __builtin_bit_cast(bf16x8, w);
;         }
; #pragma unroll
;         for (int eb = 0; eb < NEB; ++eb) {
;           const bf16x8 a = *(const bf16x8*)(vb0 + eb * 32 * VP + (32 * kb + 16 * s2) * 2);
; #pragma unroll
;           for (int qb = 0; qb < 2; ++qb) o[qb][eb] = MFMA(a, pq[qb], o[qb][eb]);
;         }
;       }
;   }
	v_mfma_f32_32x32x16_bf16 v[48:63], v[80:83], v[192:195], v[48:63]
	v_exp_f32_e32 v105, v91
	v_exp_f32_e32 v119, v92
	v_exp_f32_e32 v125, v93
	v_mfma_f32_32x32x16_bf16 v[16:31], v[80:83], v[84:87], v[16:31]
	ds_read_b128 v[80:83], v185 offset:32288
	v_exp_f32_e32 v123, v94
	v_exp_f32_e32 v92, v69
	v_exp_f32_e32 v127, v95
	s_waitcnt lgkmcnt(1)
	v_mfma_f32_32x32x16_bf16 v[0:15], v[200:203], v[84:87], v[0:15]
	v_exp_f32_e32 v93, v70
	v_add_f32_e32 v66, v207, v66
	v_add_f32_e32 v67, v109, v206
	v_add_f32_e32 v66, v208, v66
	v_add_f32_e32 v67, v111, v67
	v_add_f32_e32 v66, v212, v66
	v_add_f32_e32 v67, v92, v67
	v_mfma_f32_32x32x16_bf16 v[32:47], v[200:203], v[192:195], v[32:47]
	v_cvt_pk_bf16_f32 v84, v180, v116
	v_cvt_pk_bf16_f32 v85, v98, v104
	v_cvt_pk_bf16_f32 v86, v118, v124
	v_cvt_pk_bf16_f32 v87, v122, v126
	v_cvt_pk_bf16_f32 v88, v181, v117
	v_cvt_pk_bf16_f32 v89, v99, v105
	v_cvt_pk_bf16_f32 v90, v119, v125
	v_cvt_pk_bf16_f32 v91, v123, v127
	v_add_f32_e32 v113, v213, v66
	v_add_f32_e32 v103, v93, v67
	ds_read_b128 v[66:69], v185 offset:27712
	v_mfma_f32_32x32x16_bf16 v[48:63], v[196:199], v[84:87], v[48:63]
	v_exp_f32_e32 v179, v71
	v_mov_b32_e32 v70, v72
	v_exp_f32_e32 v115, v73
	v_cvt_pk_bf16_f32 v71, v121, v109
	v_cvt_pk_bf16_f32 v72, v111, v92
	v_cvt_pk_bf16_f32 v73, v93, v179
	v_mfma_f32_32x32x16_bf16 v[16:31], v[196:199], v[88:91], v[16:31]
	s_waitcnt lgkmcnt(1)
	v_mfma_f32_32x32x16_bf16 v[0:15], v[80:83], v[88:91], v[0:15]
	ds_read_b128 v[88:91], v185 offset:32320
	v_mfma_f32_32x32x16_bf16 v[32:47], v[80:83], v[84:87], v[32:47]
	v_cvt_pk_bf16_f32 v80, v186, v97
	v_exp_f32_e32 v97, v70
	v_cvt_pk_bf16_f32 v70, v107, v65
	v_cvt_pk_bf16_f32 v81, v187, v190
	v_cvt_pk_bf16_f32 v82, v204, v101
	v_cvt_pk_bf16_f32 v83, v205, v178
	v_exp_f32_e32 v101, v74
	ds_read_b128 v[84:87], v185 offset:27744
	s_waitcnt lgkmcnt(2)
	v_mfma_f32_32x32x16_bf16 v[48:63], v[66:69], v[80:83], v[48:63]
	v_exp_f32_e32 v107, v75
	v_exp_f32_e32 v121, v76
	v_exp_f32_e32 v109, v77
	v_exp_f32_e32 v111, v78
	v_mfma_f32_32x32x16_bf16 v[16:31], v[66:69], v[70:73], v[16:31]
	ds_read_b128 v[66:69], v185 offset:32352
	v_exp_f32_e32 v65, v79
	v_add_f32_e32 v74, v178, v102
	v_add_f32_e32 v75, v179, v103
	s_nop 0
	v_add_f32_e32 v74, v96, v74
	v_add_f32_e32 v75, v97, v75
	s_waitcnt lgkmcnt(2)
	v_mfma_f32_32x32x16_bf16 v[32:47], v[88:91], v[80:83], v[32:47]
	v_add_f32_e64 v80, v114, v74
	v_add_f32_e64 v81, v115, v75
	v_cvt_pk_bf16_f32 v74, v97, v115
	v_cvt_pk_bf16_f32 v75, v101, v107
	v_add_f32_e64 v80, v100, v80
	v_add_f32_e64 v81, v101, v81
	v_add_f32_e32 v80, v106, v80
	v_add_f32_e32 v81, v107, v81
	v_mfma_f32_32x32x16_bf16 v[0:15], v[88:91], v[70:73], v[0:15]
	v_add_f32_e64 v70, v176, v112
	v_add_f32_e64 v71, v177, v113
	v_cvt_pk_bf16_f32 v72, v120, v108
	v_add_f32_e64 v76, v180, v70
	v_add_f32_e64 v77, v181, v71
	v_cvt_pk_bf16_f32 v70, v96, v114
	v_cvt_pk_bf16_f32 v71, v100, v106
	v_cvt_pk_bf16_f32 v73, v110, v64
	v_add_f32_e32 v78, v116, v76
	v_add_f32_e32 v79, v117, v77
	v_cvt_pk_bf16_f32 v76, v121, v109
	v_cvt_pk_bf16_f32 v77, v111, v65
	s_waitcnt lgkmcnt(1)
	v_mfma_f32_32x32x16_bf16 v[48:63], v[84:87], v[70:73], v[48:63]
	v_add_f32_e64 v78, v98, v78
	v_add_f32_e64 v79, v99, v79
	v_add_f32_e64 v80, v120, v80
	v_add_f32_e64 v81, v121, v81
	v_add_f32_e64 v78, v104, v78
	v_add_f32_e64 v79, v105, v79
	v_add_f32_e32 v78, v118, v78
	v_add_f32_e32 v79, v119, v79
	s_nop 0
	v_add_f32_e32 v78, v124, v78
	v_add_f32_e32 v79, v125, v79
	v_mfma_f32_32x32x16_bf16 v[16:31], v[84:87], v[74:77], v[16:31]
	s_waitcnt lgkmcnt(0)
	v_mfma_f32_32x32x16_bf16 v[32:47], v[66:69], v[70:73], v[32:47]
	v_add_f32_e64 v70, v108, v80
	v_add_f32_e64 v71, v109, v81
	v_add_f32_e64 v72, v122, v78
	v_add_f32_e64 v73, v123, v79
	v_add_f32_e64 v70, v110, v70
	v_add_f32_e64 v71, v111, v71
	v_add_f32_e32 v72, v126, v72
	v_add_f32_e32 v73, v127, v73
	v_add_f32_e32 v64, v64, v70
	v_add_f32_e32 v65, v65, v71
	s_nop 0
	v_add_f32_e32 v64, v72, v64
	v_add_f32_e32 v65, v73, v65
	v_mfma_f32_32x32x16_bf16 v[0:15], v[66:69], v[74:77], v[0:15]
	v_add_f32_e64 v174, v174, v64
	v_add_f32_e64 v175, v175, v65
	s_add_i32 s6, s6, 2
	s_cmpk_lt_i32 s6, 0x7e
	s_cbranch_scc1 .LBB0_1430
	s_waitcnt lgkmcnt(0)
	s_barrier
	ds_read_b128 v[64:67], v169
	ds_read_b128 v[176:179], v169 offset:32
	ds_read_b128 v[68:71], v169 offset:4608
	ds_read_b128 v[192:195], v169 offset:4640
	s_waitcnt lgkmcnt(3)
	v_mfma_f32_32x32x16_bf16 v[112:127], v[64:67], v[128:131], v[236:251]
	s_waitcnt lgkmcnt(1)
	v_mfma_f32_32x32x16_bf16 v[96:111], v[68:71], v[128:131], v[236:251]
	v_mfma_f32_32x32x16_bf16 v[80:95], v[64:67], v[144:147], v[236:251]
	v_mfma_f32_32x32x16_bf16 v[64:79], v[68:71], v[144:147], v[236:251]
	v_mfma_f32_32x32x16_bf16 v[112:127], v[176:179], v[132:135], v[112:127]
	s_waitcnt lgkmcnt(0)
	v_mfma_f32_32x32x16_bf16 v[96:111], v[192:195], v[132:135], v[96:111]
	v_mfma_f32_32x32x16_bf16 v[80:95], v[176:179], v[148:151], v[80:95]
	v_mfma_f32_32x32x16_bf16 v[64:79], v[192:195], v[148:151], v[64:79]
	ds_read_b128 v[176:179], v169 offset:64
	ds_read_b128 v[192:195], v169 offset:96
	ds_read_b128 v[196:199], v169 offset:4672
	ds_read_b128 v[200:203], v169 offset:4704
	s_waitcnt lgkmcnt(3)
	v_mfma_f32_32x32x16_bf16 v[112:127], v[176:179], v[136:139], v[112:127]
	s_waitcnt lgkmcnt(1)
	v_mfma_f32_32x32x16_bf16 v[96:111], v[196:199], v[136:139], v[96:111]
	v_mfma_f32_32x32x16_bf16 v[80:95], v[176:179], v[152:155], v[80:95]
	v_mfma_f32_32x32x16_bf16 v[64:79], v[196:199], v[152:155], v[64:79]
	v_mfma_f32_32x32x16_bf16 v[112:127], v[192:195], v[140:143], v[112:127]
	s_waitcnt lgkmcnt(0)
; __device__ __forceinline__ float fexp2(float x) { return __builtin_amdgcn_exp2f(x); }
; template <int DQK, int DV>
; __device__ __forceinline__ void attn_pass2(const bf16_t* __restrict__ qh, const bf16_t* __restrict__ kh, const bf16_t* __restrict__ vth, int q0, char* smem, f32x16 (&o)[2][DV / 32], float kmax, int wvp) {
;     ...
;   for (int kt = 0; kt < NT; ++kt) {
;     const int cur = kt & 1;
;     __syncthreads();
;     if (kt + 1 < NT) { STOREKV(cur ^ 1); if (kt + 2 < NT) LOADKV(kt + 2); }
;     f32x16 s[2][2];
;     const char* kb0 = sK + cur * KSB + kofs;
; #pragma unroll
;     for (int ks = 0; ks < NKS; ++ks) {
;       const bf16x8 a0 = *(const bf16x8*)(kb0 + ks * 32), a1 = *(const bf16x8*)(kb0 + 32 * KP + ks * 32);
; #pragma unroll
;       for (int qb = 0; qb < 2; ++qb) {
;         if (ks == 0) {
;           f32x16 z;
; #pragma unroll
;           for (int i = 0; i < 16; ++i) z[i] = 0.f;
;           s[qb][0] = MFMA(a0, qf[qb][0], z); s[qb][1] = MFMA(a1, qf[qb][0], z);
;         } else { s[qb][0] = MFMA(a0, qf[qb][ks], s[qb][0]); s[qb][1] = MFMA(a1, qf[qb][ks], s[qb][1]); }
;       }
;     }
;     __builtin_amdgcn_sched_barrier(0);
; #pragma unroll
;     for (int qb = 0; qb < 2; ++qb) {
;       float rs0 = 0.f, rs1 = 0.f;
; #pragma unroll
;       for (int i = 0; i < 16; ++i) { s[qb][0][i] = fexp2(s[qb][0][i] - mref[qb]); s[qb][1][i] = fexp2(s[qb][1][i] - mref[qb]); rs0 += s[qb][0][i]; rs1 += s[qb][1][i]; }
;       l_run[qb] += rs0 + rs1;
;     }
;     const char* vb0 = sV + cur * VSB + vofs;
; #pragma unroll
;     for (int kb = 0; kb < 2; ++kb)
; #pragma unroll
;       for (int s2 = 0; s2 < 2; ++s2) {
;         bf16x8 pq[2];
; #pragma unroll
;         for (int qb = 0; qb < 2; ++qb) {
;           u32x4 w;
;           w.x = pk2(s[qb][kb][8 * s2 + 0], s[qb][kb][8 * s2 + 1]); w.y = pk2(s[qb][kb][8 * s2 + 2], s[qb][kb][8 * s2 + 3]);
;           w.z = pk2(s[qb][kb][8 * s2 + 4], s[qb][kb][8 * s2 + 5]); w.w = pk2(s[qb][kb][8 * s2 + 6], s[qb][kb][8 * s2 + 7]);
;           pq[qb] = __builtin_bit_cast(bf16x8, w);
;         }
; #pragma unroll
;         for (int eb = 0; eb < NEB; ++eb) {
;           const bf16x8 a = *(const bf16x8*)(vb0 + eb * 32 * VP + (32 * kb + 16 * s2) * 2);
; #pragma unroll
;           for (int qb = 0; qb < 2; ++qb) o[qb][eb] = MFMA(a, pq[qb], o[qb][eb]);
;         }
;       }
;   }
	v_mfma_f32_32x32x16_bf16 v[96:111], v[200:203], v[140:143], v[96:111]
	v_mfma_f32_32x32x16_bf16 v[80:95], v[192:195], v[156:159], v[80:95]
	v_mfma_f32_32x32x16_bf16 v[64:79], v[200:203], v[156:159], v[64:79]
	s_waitcnt vmcnt(1)
	ds_write_b128 v184, v[160:163] offset:9216
	s_waitcnt vmcnt(0)
	ds_write_b128 v168, v[164:167] offset:27648
	s_nop 5
	v_exp_f32_e32 v186, v96
	v_exp_f32_e32 v97, v97
	v_exp_f32_e32 v177, v112
	v_exp_f32_e32 v113, v113
	v_exp_f32_e32 v179, v114
	v_exp_f32_e32 v187, v98
	v_add_f32_e32 v98, v97, v186
	v_exp_f32_e32 v115, v115
	v_exp_f32_e32 v190, v99
	v_exp_f32_e32 v204, v100
	v_exp_f32_e32 v99, v116
	v_exp_f32_e32 v117, v117
	v_add_f32_e32 v96, v113, v177
	v_exp_f32_e32 v101, v101
	v_add_f32_e32 v96, v179, v96
	v_exp_f32_e32 v181, v118
	v_add_f32_e32 v96, v115, v96
	v_add_f32_e32 v96, v99, v96
	v_add_f32_e32 v96, v117, v96
	v_add_f32_e32 v112, v181, v96
	v_exp_f32_e32 v176, v119
	v_exp_f32_e32 v178, v103
	v_add_f32_e32 v98, v187, v98
	v_exp_f32_e32 v205, v102
	v_exp_f32_e32 v180, v120
	v_exp_f32_e32 v96, v104
	v_exp_f32_e32 v104, v123
	v_add_f32_e32 v98, v190, v98
	v_exp_f32_e32 v100, v106
	v_exp_f32_e32 v106, v107
	v_add_f32_e32 v98, v204, v98
	v_exp_f32_e32 v118, v124
	v_add_f32_e32 v98, v101, v98
	v_exp_f32_e32 v120, v108
	v_add_f32_e32 v102, v205, v98
	v_exp_f32_e32 v124, v125
	v_exp_f32_e32 v116, v121
	v_exp_f32_e32 v108, v109
	v_exp_f32_e32 v114, v105
	v_exp_f32_e32 v98, v122
	v_exp_f32_e32 v122, v126
	v_exp_f32_e32 v110, v110
	v_exp_f32_e32 v126, v127
	v_exp_f32_e32 v103, v80
	v_exp_f32_e32 v107, v64
	v_exp_f32_e32 v109, v81
	v_exp_f32_e32 v65, v65
	v_exp_f32_e32 v121, v66
	v_add_f32_e32 v66, v109, v103
	v_add_f32_e32 v80, v65, v107
	v_add_f32_e32 v206, v121, v80
	v_exp_f32_e32 v207, v83
	v_exp_f32_e32 v64, v111
	v_exp_f32_e32 v111, v82
	v_exp_f32_e32 v208, v84
	ds_read_b128 v[80:83], v185 offset:18432
	ds_read_b128 v[196:199], v185 offset:18464
	ds_read_b128 v[200:203], v185 offset:23040
	v_exp_f32_e32 v212, v85
	v_exp_f32_e32 v213, v86
	v_cvt_pk_bf16_f32 v192, v177, v113
	v_exp_f32_e32 v177, v87
	v_cvt_pk_bf16_f32 v84, v103, v109
	v_exp_f32_e32 v109, v67
	v_add_f32_e32 v66, v111, v66
	v_cvt_pk_bf16_f32 v85, v111, v207
	v_exp_f32_e32 v111, v68
	v_cvt_pk_bf16_f32 v195, v181, v176
	v_exp_f32_e32 v181, v88
	v_cvt_pk_bf16_f32 v194, v99, v117
	v_exp_f32_e32 v117, v89
	v_cvt_pk_bf16_f32 v193, v179, v115
	v_cvt_pk_bf16_f32 v86, v208, v212
	v_cvt_pk_bf16_f32 v87, v213, v177
	v_exp_f32_e32 v99, v90
	s_waitcnt lgkmcnt(2)
	v_mfma_f32_32x32x16_bf16 v[48:63], v[80:83], v[192:195], v[48:63]
	v_exp_f32_e32 v105, v91
	v_exp_f32_e32 v119, v92
	v_exp_f32_e32 v125, v93
	v_mfma_f32_32x32x16_bf16 v[16:31], v[80:83], v[84:87], v[16:31]
	ds_read_b128 v[80:83], v185 offset:23072
	v_exp_f32_e32 v123, v94
	v_exp_f32_e32 v92, v69
	v_exp_f32_e32 v127, v95
	s_waitcnt lgkmcnt(1)
	v_mfma_f32_32x32x16_bf16 v[0:15], v[200:203], v[84:87], v[0:15]
	v_exp_f32_e32 v93, v70
	v_add_f32_e32 v66, v207, v66
	v_add_f32_e32 v67, v109, v206
	v_add_f32_e32 v66, v208, v66
	v_add_f32_e32 v67, v111, v67
	v_add_f32_e32 v66, v212, v66
	v_add_f32_e32 v67, v92, v67
	v_mfma_f32_32x32x16_bf16 v[32:47], v[200:203], v[192:195], v[32:47]
	v_cvt_pk_bf16_f32 v84, v180, v116
	v_cvt_pk_bf16_f32 v85, v98, v104
	v_cvt_pk_bf16_f32 v86, v118, v124
	v_cvt_pk_bf16_f32 v87, v122, v126
	v_cvt_pk_bf16_f32 v88, v181, v117
	v_cvt_pk_bf16_f32 v89, v99, v105
	v_cvt_pk_bf16_f32 v90, v119, v125
	v_cvt_pk_bf16_f32 v91, v123, v127
	v_add_f32_e32 v113, v213, v66
	v_add_f32_e32 v103, v93, v67
	ds_read_b128 v[66:69], v185 offset:18496
	v_mfma_f32_32x32x16_bf16 v[48:63], v[196:199], v[84:87], v[48:63]
	v_exp_f32_e32 v179, v71
	v_mov_b32_e32 v70, v72
	v_exp_f32_e32 v115, v73
	v_cvt_pk_bf16_f32 v71, v121, v109
	v_cvt_pk_bf16_f32 v72, v111, v92
	v_cvt_pk_bf16_f32 v73, v93, v179
	v_mfma_f32_32x32x16_bf16 v[16:31], v[196:199], v[88:91], v[16:31]
	s_waitcnt lgkmcnt(1)
	v_mfma_f32_32x32x16_bf16 v[0:15], v[80:83], v[88:91], v[0:15]
	ds_read_b128 v[88:91], v185 offset:23104
	v_mfma_f32_32x32x16_bf16 v[32:47], v[80:83], v[84:87], v[32:47]
	v_cvt_pk_bf16_f32 v80, v186, v97
	v_exp_f32_e32 v97, v70
	v_cvt_pk_bf16_f32 v70, v107, v65
	v_cvt_pk_bf16_f32 v81, v187, v190
	v_cvt_pk_bf16_f32 v82, v204, v101
	v_cvt_pk_bf16_f32 v83, v205, v178
	v_exp_f32_e32 v101, v74
	ds_read_b128 v[84:87], v185 offset:18528
	s_waitcnt lgkmcnt(2)
	v_mfma_f32_32x32x16_bf16 v[48:63], v[66:69], v[80:83], v[48:63]
	v_exp_f32_e32 v107, v75
	v_exp_f32_e32 v121, v76
	v_exp_f32_e32 v109, v77
	v_exp_f32_e32 v111, v78
	v_mfma_f32_32x32x16_bf16 v[16:31], v[66:69], v[70:73], v[16:31]
	ds_read_b128 v[66:69], v185 offset:23136
	v_exp_f32_e32 v65, v79
	v_add_f32_e32 v74, v178, v102
	v_add_f32_e32 v75, v179, v103
	s_nop 0
	v_add_f32_e32 v74, v96, v74
	v_add_f32_e32 v75, v97, v75
	s_waitcnt lgkmcnt(2)
	v_mfma_f32_32x32x16_bf16 v[32:47], v[88:91], v[80:83], v[32:47]
	v_add_f32_e64 v80, v114, v74
	v_add_f32_e64 v81, v115, v75
	v_cvt_pk_bf16_f32 v74, v97, v115
	v_cvt_pk_bf16_f32 v75, v101, v107
	v_add_f32_e64 v80, v100, v80
	v_add_f32_e64 v81, v101, v81
	v_add_f32_e32 v80, v106, v80
	v_add_f32_e32 v81, v107, v81
	v_mfma_f32_32x32x16_bf16 v[0:15], v[88:91], v[70:73], v[0:15]
	v_add_f32_e64 v70, v176, v112
	v_add_f32_e64 v71, v177, v113
	v_cvt_pk_bf16_f32 v72, v120, v108
	v_add_f32_e64 v76, v180, v70
	v_add_f32_e64 v77, v181, v71
	v_cvt_pk_bf16_f32 v70, v96, v114
	v_cvt_pk_bf16_f32 v71, v100, v106
	v_cvt_pk_bf16_f32 v73, v110, v64
	v_add_f32_e32 v78, v116, v76
	v_add_f32_e32 v79, v117, v77
	v_cvt_pk_bf16_f32 v76, v121, v109
	v_cvt_pk_bf16_f32 v77, v111, v65
	s_waitcnt lgkmcnt(1)
	v_mfma_f32_32x32x16_bf16 v[48:63], v[84:87], v[70:73], v[48:63]
	v_add_f32_e64 v78, v98, v78
	v_add_f32_e64 v79, v99, v79
	v_add_f32_e64 v80, v120, v80
	v_add_f32_e64 v81, v121, v81
	v_add_f32_e64 v78, v104, v78
	v_add_f32_e64 v79, v105, v79
	v_add_f32_e32 v78, v118, v78
	v_add_f32_e32 v79, v119, v79
	s_nop 0
	v_add_f32_e32 v78, v124, v78
	v_add_f32_e32 v79, v125, v79
	v_mfma_f32_32x32x16_bf16 v[16:31], v[84:87], v[74:77], v[16:31]
	s_waitcnt lgkmcnt(0)
	v_mfma_f32_32x32x16_bf16 v[32:47], v[66:69], v[70:73], v[32:47]
	v_add_f32_e64 v70, v108, v80
	v_add_f32_e64 v71, v109, v81
	v_add_f32_e64 v72, v122, v78
	v_add_f32_e64 v73, v123, v79
	v_add_f32_e64 v70, v110, v70
	v_add_f32_e64 v71, v111, v71
	v_add_f32_e32 v72, v126, v72
	v_add_f32_e32 v73, v127, v73
	v_add_f32_e32 v64, v64, v70
	v_add_f32_e32 v65, v65, v71
	s_nop 0
	v_add_f32_e32 v64, v72, v64
	v_add_f32_e32 v65, v73, v65
	v_mfma_f32_32x32x16_bf16 v[0:15], v[66:69], v[74:77], v[0:15]
	v_add_f32_e64 v174, v174, v64
	v_add_f32_e64 v175, v175, v65
	s_waitcnt lgkmcnt(0)
	s_barrier
; __device__ __forceinline__ float fexp2(float x) { return __builtin_amdgcn_exp2f(x); }
; template <int DQK, int DV>
; __device__ __forceinline__ void attn_pass2(const bf16_t* __restrict__ qh, const bf16_t* __restrict__ kh, const bf16_t* __restrict__ vth, int q0, char* smem, f32x16 (&o)[2][DV / 32], float kmax, int wvp) {
;     ...
;   for (int kt = 0; kt < NT; ++kt) {
;     const int cur = kt & 1;
;     __syncthreads();
;     if (kt + 1 < NT) { STOREKV(cur ^ 1); if (kt + 2 < NT) LOADKV(kt + 2); }
;     f32x16 s[2][2];
;     const char* kb0 = sK + cur * KSB + kofs;
; #pragma unroll
;     for (int ks = 0; ks < NKS; ++ks) {
;       const bf16x8 a0 = *(const bf16x8*)(kb0 + ks * 32), a1 = *(const bf16x8*)(kb0 + 32 * KP + ks * 32);
; #pragma unroll
;       for (int qb = 0; qb < 2; ++qb) {
;         if (ks == 0) {
;           f32x16 z;
; #pragma unroll
;           for (int i = 0; i < 16; ++i) z[i] = 0.f;
;           s[qb][0] = MFMA(a0, qf[qb][0], z); s[qb][1] = MFMA(a1, qf[qb][0], z);
;         } else { s[qb][0] = MFMA(a0, qf[qb][ks], s[qb][0]); s[qb][1] = MFMA(a1, qf[qb][ks], s[qb][1]); }
;       }
;     }
;     __builtin_amdgcn_sched_barrier(0);
; #pragma unroll
;     for (int qb = 0; qb < 2; ++qb) {
;       float rs0 = 0.f, rs1 = 0.f;
; #pragma unroll
;       for (int i = 0; i < 16; ++i) { s[qb][0][i] = fexp2(s[qb][0][i] - mref[qb]); s[qb][1][i] = fexp2(s[qb][1][i] - mref[qb]); rs0 += s[qb][0][i]; rs1 += s[qb][1][i]; }
;       l_run[qb] += rs0 + rs1;
;     }
;     const char* vb0 = sV + cur * VSB + vofs;
; #pragma unroll
;     for (int kb = 0; kb < 2; ++kb)
; #pragma unroll
;       for (int s2 = 0; s2 < 2; ++s2) {
;         bf16x8 pq[2];
; #pragma unroll
;         for (int qb = 0; qb < 2; ++qb) {
;           u32x4 w;
;           w.x = pk2(s[qb][kb][8 * s2 + 0], s[qb][kb][8 * s2 + 1]); w.y = pk2(s[qb][kb][8 * s2 + 2], s[qb][kb][8 * s2 + 3]);
;           w.z = pk2(s[qb][kb][8 * s2 + 4], s[qb][kb][8 * s2 + 5]); w.w = pk2(s[qb][kb][8 * s2 + 6], s[qb][kb][8 * s2 + 7]);
;           pq[qb] = __builtin_bit_cast(bf16x8, w);
;         }
; #pragma unroll
;         for (int eb = 0; eb < NEB; ++eb) {
;           const bf16x8 a = *(const bf16x8*)(vb0 + eb * 32 * VP + (32 * kb + 16 * s2) * 2);
; #pragma unroll
;           for (int qb = 0; qb < 2; ++qb) o[qb][eb] = MFMA(a, pq[qb], o[qb][eb]);
;         }
;       }
;   }
	ds_read_b128 v[64:67], v169 offset:9216
	ds_read_b128 v[176:179], v169 offset:9248
	ds_read_b128 v[68:71], v169 offset:13824
	ds_read_b128 v[192:195], v169 offset:13856
	s_waitcnt lgkmcnt(3)
	v_mfma_f32_32x32x16_bf16 v[112:127], v[64:67], v[128:131], v[236:251]
	s_waitcnt lgkmcnt(1)
	v_mfma_f32_32x32x16_bf16 v[96:111], v[68:71], v[128:131], v[236:251]
	v_mfma_f32_32x32x16_bf16 v[80:95], v[64:67], v[144:147], v[236:251]
	v_mfma_f32_32x32x16_bf16 v[64:79], v[68:71], v[144:147], v[236:251]
	v_mfma_f32_32x32x16_bf16 v[112:127], v[176:179], v[132:135], v[112:127]
	s_waitcnt lgkmcnt(0)
	v_mfma_f32_32x32x16_bf16 v[96:111], v[192:195], v[132:135], v[96:111]
	v_mfma_f32_32x32x16_bf16 v[80:95], v[176:179], v[148:151], v[80:95]
	v_mfma_f32_32x32x16_bf16 v[64:79], v[192:195], v[148:151], v[64:79]
	ds_read_b128 v[176:179], v169 offset:9280
	ds_read_b128 v[192:195], v169 offset:9312
	ds_read_b128 v[196:199], v169 offset:13888
	ds_read_b128 v[200:203], v169 offset:13920
	s_waitcnt lgkmcnt(3)
	v_mfma_f32_32x32x16_bf16 v[112:127], v[176:179], v[136:139], v[112:127]
	s_waitcnt lgkmcnt(1)
	v_mfma_f32_32x32x16_bf16 v[96:111], v[196:199], v[136:139], v[96:111]
	v_mfma_f32_32x32x16_bf16 v[80:95], v[176:179], v[152:155], v[80:95]
	v_mfma_f32_32x32x16_bf16 v[64:79], v[196:199], v[152:155], v[64:79]
	v_mfma_f32_32x32x16_bf16 v[112:127], v[192:195], v[140:143], v[112:127]
	s_waitcnt lgkmcnt(0)
	v_mfma_f32_32x32x16_bf16 v[96:111], v[200:203], v[140:143], v[96:111]
	v_mfma_f32_32x32x16_bf16 v[80:95], v[192:195], v[156:159], v[80:95]
	v_mfma_f32_32x32x16_bf16 v[64:79], v[200:203], v[156:159], v[64:79]
	s_nop 9
	v_exp_f32_e32 v186, v96
	v_exp_f32_e32 v97, v97
	v_exp_f32_e32 v177, v112
	v_exp_f32_e32 v113, v113
	v_exp_f32_e32 v179, v114
	v_exp_f32_e32 v187, v98
	v_add_f32_e32 v98, v97, v186
	v_exp_f32_e32 v115, v115
	v_exp_f32_e32 v190, v99
	v_exp_f32_e32 v204, v100
	v_exp_f32_e32 v99, v116
	v_exp_f32_e32 v117, v117
	v_add_f32_e32 v96, v113, v177
	v_exp_f32_e32 v101, v101
	v_add_f32_e32 v96, v179, v96
	v_exp_f32_e32 v181, v118
	v_add_f32_e32 v96, v115, v96
	v_add_f32_e32 v96, v99, v96
	v_add_f32_e32 v96, v117, v96
	v_add_f32_e32 v112, v181, v96
	v_exp_f32_e32 v176, v119
	v_exp_f32_e32 v178, v103
	v_add_f32_e32 v98, v187, v98
	v_exp_f32_e32 v205, v102
	v_exp_f32_e32 v180, v120
	v_exp_f32_e32 v96, v104
	v_exp_f32_e32 v104, v123
	v_add_f32_e32 v98, v190, v98
	v_exp_f32_e32 v100, v106
	v_exp_f32_e32 v106, v107
	v_add_f32_e32 v98, v204, v98
	v_exp_f32_e32 v118, v124
	v_add_f32_e32 v98, v101, v98
	v_exp_f32_e32 v120, v108
	v_add_f32_e32 v102, v205, v98
	v_exp_f32_e32 v124, v125
	v_exp_f32_e32 v116, v121
	v_exp_f32_e32 v108, v109
	v_exp_f32_e32 v114, v105
	v_exp_f32_e32 v98, v122
	v_exp_f32_e32 v122, v126
	v_exp_f32_e32 v110, v110
	v_exp_f32_e32 v126, v127
	v_exp_f32_e32 v103, v80
	v_exp_f32_e32 v107, v64
	v_exp_f32_e32 v109, v81
	v_exp_f32_e32 v65, v65
	v_exp_f32_e32 v121, v66
	v_add_f32_e32 v66, v109, v103
	v_add_f32_e32 v80, v65, v107
	v_add_f32_e32 v206, v121, v80
	v_exp_f32_e32 v207, v83
	v_exp_f32_e32 v64, v111
	v_exp_f32_e32 v111, v82
	v_exp_f32_e32 v208, v84
	ds_read_b128 v[80:83], v185 offset:27648
	ds_read_b128 v[196:199], v185 offset:27680
	ds_read_b128 v[200:203], v185 offset:32256
	v_exp_f32_e32 v212, v85
	v_exp_f32_e32 v213, v86
	v_cvt_pk_bf16_f32 v192, v177, v113
	v_exp_f32_e32 v177, v87
	v_cvt_pk_bf16_f32 v84, v103, v109
	v_exp_f32_e32 v109, v67
	v_add_f32_e32 v66, v111, v66
	v_cvt_pk_bf16_f32 v85, v111, v207
	v_exp_f32_e32 v111, v68
	v_cvt_pk_bf16_f32 v195, v181, v176
	v_exp_f32_e32 v181, v88
	v_cvt_pk_bf16_f32 v194, v99, v117
	v_exp_f32_e32 v117, v89
	v_cvt_pk_bf16_f32 v193, v179, v115
	v_cvt_pk_bf16_f32 v86, v208, v212
	v_cvt_pk_bf16_f32 v87, v213, v177
	v_exp_f32_e32 v99, v90
	s_waitcnt lgkmcnt(2)
	v_mfma_f32_32x32x16_bf16 v[48:63], v[80:83], v[192:195], v[48:63]
	v_exp_f32_e32 v105, v91
	v_exp_f32_e32 v119, v92
	v_exp_f32_e32 v125, v93
	v_mfma_f32_32x32x16_bf16 v[16:31], v[80:83], v[84:87], v[16:31]
	ds_read_b128 v[80:83], v185 offset:32288
	v_exp_f32_e32 v123, v94
	v_exp_f32_e32 v92, v69
	v_exp_f32_e32 v127, v95
	s_waitcnt lgkmcnt(1)
; __device__ __forceinline__ float fexp2(float x) { return __builtin_amdgcn_exp2f(x); }
; template <int DQK, int DV>
; __device__ __forceinline__ void attn_pass2(const bf16_t* __restrict__ qh, const bf16_t* __restrict__ kh, const bf16_t* __restrict__ vth, int q0, char* smem, f32x16 (&o)[2][DV / 32], float kmax, int wvp) {
;     ...
;   for (int kt = 0; kt < NT; ++kt) {
;     const int cur = kt & 1;
;     __syncthreads();
;     if (kt + 1 < NT) { STOREKV(cur ^ 1); if (kt + 2 < NT) LOADKV(kt + 2); }
;     f32x16 s[2][2];
;     const char* kb0 = sK + cur * KSB + kofs;
; #pragma unroll
;     for (int ks = 0; ks < NKS; ++ks) {
;       const bf16x8 a0 = *(const bf16x8*)(kb0 + ks * 32), a1 = *(const bf16x8*)(kb0 + 32 * KP + ks * 32);
; #pragma unroll
;       for (int qb = 0; qb < 2; ++qb) {
;         if (ks == 0) {
;           f32x16 z;
; #pragma unroll
;           for (int i = 0; i < 16; ++i) z[i] = 0.f;
;           s[qb][0] = MFMA(a0, qf[qb][0], z); s[qb][1] = MFMA(a1, qf[qb][0], z);
;         } else { s[qb][0] = MFMA(a0, qf[qb][ks], s[qb][0]); s[qb][1] = MFMA(a1, qf[qb][ks], s[qb][1]); }
;       }
;     }
;     __builtin_amdgcn_sched_barrier(0);
; #pragma unroll
;     for (int qb = 0; qb < 2; ++qb) {
;       float rs0 = 0.f, rs1 = 0.f;
; #pragma unroll
;       for (int i = 0; i < 16; ++i) { s[qb][0][i] = fexp2(s[qb][0][i] - mref[qb]); s[qb][1][i] = fexp2(s[qb][1][i] - mref[qb]); rs0 += s[qb][0][i]; rs1 += s[qb][1][i]; }
;       l_run[qb] += rs0 + rs1;
;     }
;     const char* vb0 = sV + cur * VSB + vofs;
; #pragma unroll
;     for (int kb = 0; kb < 2; ++kb)
; #pragma unroll
;       for (int s2 = 0; s2 < 2; ++s2) {
;         bf16x8 pq[2];
; #pragma unroll
;         for (int qb = 0; qb < 2; ++qb) {
;           u32x4 w;
;           w.x = pk2(s[qb][kb][8 * s2 + 0], s[qb][kb][8 * s2 + 1]); w.y = pk2(s[qb][kb][8 * s2 + 2], s[qb][kb][8 * s2 + 3]);
;           w.z = pk2(s[qb][kb][8 * s2 + 4], s[qb][kb][8 * s2 + 5]); w.w = pk2(s[qb][kb][8 * s2 + 6], s[qb][kb][8 * s2 + 7]);
;           pq[qb] = __builtin_bit_cast(bf16x8, w);
;         }
; #pragma unroll
;         for (int eb = 0; eb < NEB; ++eb) {
;           const bf16x8 a = *(const bf16x8*)(vb0 + eb * 32 * VP + (32 * kb + 16 * s2) * 2);
; #pragma unroll
;           for (int qb = 0; qb < 2; ++qb) o[qb][eb] = MFMA(a, pq[qb], o[qb][eb]);
;         }
;       }
;   }
	v_mfma_f32_32x32x16_bf16 v[0:15], v[200:203], v[84:87], v[0:15]
	v_exp_f32_e32 v93, v70
	v_add_f32_e32 v66, v207, v66
	v_add_f32_e32 v67, v109, v206
	v_add_f32_e32 v66, v208, v66
	v_add_f32_e32 v67, v111, v67
	v_add_f32_e32 v66, v212, v66
	v_add_f32_e32 v67, v92, v67
	v_mfma_f32_32x32x16_bf16 v[32:47], v[200:203], v[192:195], v[32:47]
	v_cvt_pk_bf16_f32 v84, v180, v116
	v_cvt_pk_bf16_f32 v85, v98, v104
	v_cvt_pk_bf16_f32 v86, v118, v124
	v_cvt_pk_bf16_f32 v87, v122, v126
	v_cvt_pk_bf16_f32 v88, v181, v117
	v_cvt_pk_bf16_f32 v89, v99, v105
	v_cvt_pk_bf16_f32 v90, v119, v125
	v_cvt_pk_bf16_f32 v91, v123, v127
	v_add_f32_e32 v113, v213, v66
	v_add_f32_e32 v103, v93, v67
	ds_read_b128 v[66:69], v185 offset:27712
	v_mfma_f32_32x32x16_bf16 v[48:63], v[196:199], v[84:87], v[48:63]
	v_exp_f32_e32 v179, v71
	v_mov_b32_e32 v70, v72
	v_exp_f32_e32 v115, v73
	v_cvt_pk_bf16_f32 v71, v121, v109
	v_cvt_pk_bf16_f32 v72, v111, v92
	v_cvt_pk_bf16_f32 v73, v93, v179
	v_mfma_f32_32x32x16_bf16 v[16:31], v[196:199], v[88:91], v[16:31]
	s_waitcnt lgkmcnt(1)
	v_mfma_f32_32x32x16_bf16 v[0:15], v[80:83], v[88:91], v[0:15]
	ds_read_b128 v[88:91], v185 offset:32320
	v_mfma_f32_32x32x16_bf16 v[32:47], v[80:83], v[84:87], v[32:47]
	v_cvt_pk_bf16_f32 v80, v186, v97
	v_exp_f32_e32 v97, v70
	v_cvt_pk_bf16_f32 v70, v107, v65
	v_cvt_pk_bf16_f32 v81, v187, v190
	v_cvt_pk_bf16_f32 v82, v204, v101
	v_cvt_pk_bf16_f32 v83, v205, v178
	v_exp_f32_e32 v101, v74
	ds_read_b128 v[84:87], v185 offset:27744
	s_waitcnt lgkmcnt(2)
	v_mfma_f32_32x32x16_bf16 v[48:63], v[66:69], v[80:83], v[48:63]
	v_exp_f32_e32 v107, v75
	v_exp_f32_e32 v121, v76
	v_exp_f32_e32 v109, v77
	v_exp_f32_e32 v111, v78
	v_mfma_f32_32x32x16_bf16 v[16:31], v[66:69], v[70:73], v[16:31]
	ds_read_b128 v[66:69], v185 offset:32352
	v_exp_f32_e32 v65, v79
	v_add_f32_e32 v74, v178, v102
	v_add_f32_e32 v75, v179, v103
	s_nop 0
	v_add_f32_e32 v74, v96, v74
	v_add_f32_e32 v75, v97, v75
	s_waitcnt lgkmcnt(2)
	v_mfma_f32_32x32x16_bf16 v[32:47], v[88:91], v[80:83], v[32:47]
	v_add_f32_e64 v80, v114, v74
	v_add_f32_e64 v81, v115, v75
	v_cvt_pk_bf16_f32 v74, v97, v115
	v_cvt_pk_bf16_f32 v75, v101, v107
	v_add_f32_e64 v80, v100, v80
	v_add_f32_e64 v81, v101, v81
	v_add_f32_e32 v80, v106, v80
	v_add_f32_e32 v81, v107, v81
	v_mfma_f32_32x32x16_bf16 v[0:15], v[88:91], v[70:73], v[0:15]
	v_add_f32_e64 v70, v176, v112
	v_add_f32_e64 v71, v177, v113
	v_cvt_pk_bf16_f32 v72, v120, v108
	v_add_f32_e64 v76, v180, v70
	v_add_f32_e64 v77, v181, v71
	v_cvt_pk_bf16_f32 v70, v96, v114
	v_cvt_pk_bf16_f32 v71, v100, v106
	v_cvt_pk_bf16_f32 v73, v110, v64
	v_add_f32_e32 v78, v116, v76
	v_add_f32_e32 v79, v117, v77
	v_cvt_pk_bf16_f32 v76, v121, v109
	v_cvt_pk_bf16_f32 v77, v111, v65
	s_waitcnt lgkmcnt(1)
	v_mfma_f32_32x32x16_bf16 v[48:63], v[84:87], v[70:73], v[48:63]
	v_add_f32_e64 v78, v98, v78
	v_add_f32_e64 v79, v99, v79
	v_add_f32_e64 v80, v120, v80
	v_add_f32_e64 v81, v121, v81
	v_add_f32_e64 v78, v104, v78
	v_add_f32_e64 v79, v105, v79
	v_add_f32_e32 v78, v118, v78
	v_add_f32_e32 v79, v119, v79
	s_nop 0
	v_add_f32_e32 v78, v124, v78
	v_add_f32_e32 v79, v125, v79
	v_mfma_f32_32x32x16_bf16 v[16:31], v[84:87], v[74:77], v[16:31]
	s_waitcnt lgkmcnt(0)
	v_mfma_f32_32x32x16_bf16 v[32:47], v[66:69], v[70:73], v[32:47]
	v_add_f32_e64 v70, v108, v80
	v_add_f32_e64 v71, v109, v81
	v_add_f32_e64 v72, v122, v78
	v_add_f32_e64 v73, v123, v79
	v_add_f32_e64 v70, v110, v70
	v_add_f32_e64 v71, v111, v71
	v_add_f32_e32 v72, v126, v72
	v_add_f32_e32 v73, v127, v73
	v_add_f32_e32 v64, v64, v70
	v_add_f32_e32 v65, v65, v71
	s_nop 0
	v_add_f32_e32 v64, v72, v64
	v_add_f32_e32 v65, v73, v65
	v_mfma_f32_32x32x16_bf16 v[0:15], v[66:69], v[74:77], v[0:15]
	v_add_f32_e64 v174, v174, v64
	v_add_f32_e64 v175, v175, v65
